# RWKV cumulative log-decay as an exact-f32 triangular MFMA (v_mfma_f32_16x16x4_f32) on waves 0-3 instead of a single-wave serial add chain
# baseline (speedup 1.0000x reference)
; __device__ __forceinline__ void rwkv_chain(LAS unsigned char* lds, int cid, const bf16_t* P0, const float* mu, const float* w0, const float* w2, const float* a0, const float* a2, ...
;     ...
;     const int vt = wid >> 1, tt2 = wid & 1;
;     f32x4 st[2]; st[0] = (f32x4){0.f, 0.f, 0.f, 0.f}; st[1] = st[0];
;     __syncthreads();
;     const bf16_t* Pb = P0 + (size_t)b * SEQ * ABPAD;
;     u32x2 rc[5], rpv[5], rnx[5]; unsigned short gcv = 0, gpv = 0, gnv = 0;
;     const unsigned voff = (unsigned)((((int)threadIdx.x >> 4) * ABPAD + ((int)threadIdx.x & 15) * 4) * 2);
;     ...
;     RW_ISSUE(dir ? 127 * 32 : 0);
;     ...
;         { RW_IDS if (tid < 64) { float lw[32];
; #pragma unroll
;             for (int s = 0; s < 32; ++s) lw[s] = wS[(dir ? 31 - s : s) * 64 + tid];
; #pragma unroll
;             for (int s = 1; s < 32; ++s) lw[s] += lw[s - 1];
; #pragma unroll
;             for (int s = 0; s < 32; ++s) wS[(dir ? 31 - s : s) * 64 + tid] = lw[s]; } }
.LBB0_486:
	s_lshl_b64 s[40:41], s[12:13], 12
	s_lshl_b64 s[2:3], s[38:39], 1
	s_add_u32 s42, s57, s2
	s_addc_u32 s43, s63, s3
	s_lshl_b32 s1, s1, 2
	v_readlane_b32 s2, v253, 30
	v_readlane_b32 s3, v253, 31
	s_add_u32 s44, s2, s1
	s_addc_u32 s45, s3, 0
	s_and_b64 s[2:3], s[10:11], exec
	s_cselect_b32 s90, 1, -1
	s_lshl_b32 s1, s87, 26
	v_readlane_b32 s2, v253, 21
	v_readlane_b32 s3, v253, 22
	s_add_u32 s1, s2, s1
	s_addc_u32 s2, s3, 0
	s_lshl_b32 s0, s0, 1
	s_add_u32 s91, s1, s0
	s_addc_u32 s92, s2, 0
	s_and_b64 s[0:1], s[10:11], exec
	s_movk_i32 s8, 0x1e00
	s_movk_i32 s9, 0x1d00
	s_movk_i32 s12, 0x1b00
	s_movk_i32 s13, 0x1a00
	s_movk_i32 s14, 0x1900
	s_movk_i32 s15, 0x1800
	s_movk_i32 s16, 0x1700
	s_movk_i32 s17, 0x1600
	s_movk_i32 s46, 0x1500
	s_movk_i32 s47, 0x1400
	s_movk_i32 s48, 0x1300
	s_movk_i32 s49, 0x1200
	s_movk_i32 s5, 0x1100
	s_cselect_b32 s93, 0x1f00, 0
	s_cselect_b32 s94, s8, 0x100
	s_cselect_b32 s95, s9, 0x200
	s_cselect_b32 s96, s62, 0x300
	s_cselect_b32 s97, s12, 0x400
	s_cselect_b32 s22, s13, 0x500
	s_cselect_b32 s23, s14, 0x600
	s_cselect_b32 s18, s15, 0x700
	s_cselect_b32 s19, s16, 0x800
	s_cselect_b32 s2, s17, 0x900
	s_cselect_b32 s3, s46, 0xa00
	s_cselect_b32 s56, s47, 0xb00
	s_cselect_b32 s57, s48, 0xc00
	s_cselect_b32 s0, s49, 0xd00
	s_cselect_b32 s1, s5, 0xe00
	s_lshl_b32 s4, s87, 8
	s_and_b64 s[6:7], s[10:11], exec
	s_cselect_b32 s5, 0xe00, s5
	s_cselect_b32 s60, 0xd00, s49
	s_cselect_b32 s61, 0xc00, s48
	s_cselect_b32 s63, 0xb00, s47
	s_cselect_b32 s64, 0xa00, s46
	s_cselect_b32 s65, 0x900, s17
	s_cselect_b32 s66, 0x800, s16
	s_cselect_b32 s67, 0x700, s15
	s_cselect_b32 s68, 0x600, s14
	s_cselect_b32 s69, 0x500, s13
	s_cselect_b32 s70, 0x400, s12
	s_cselect_b32 s71, 0x300, s62
	s_cselect_b32 s72, 0x200, s9
	s_cselect_b32 s73, 0x100, s8
	s_cselect_b32 s8, 0, 0x1f00
	s_sub_i32 s9, 0, s4
	s_mov_b64 s[46:47], 0
	s_movk_i32 s6, 0xfc0
	v_mov_b32_e32 v1, v0
	v_mov_b32_e32 v2, v0
	v_mov_b32_e32 v3, v0
	v_mov_b32_e32 v4, v0
	v_mov_b32_e32 v5, v0
	v_mov_b32_e32 v6, v0
	v_mov_b32_e32 v7, v0
	v_and_b32_e32 v8, 15, v200
	v_bfe_u32 v9, v200, 4, 2
	v_mov_b32_e32 v201, 1.0
	v_add_u32_e32 v10, 0, v9
	v_cmp_le_u32_e64 s[12:13], v10, v8
	v_cmp_ge_u32_e64 s[14:15], v10, v8
	s_and_b64 vcc, s[10:11], exec
	s_cselect_b64 s[12:13], s[14:15], s[12:13]
	v_cndmask_b32_e64 v202, 0, 1.0, s[12:13]
	v_add_u32_e32 v10, 4, v9
	v_cmp_le_u32_e64 s[12:13], v10, v8
	v_cmp_ge_u32_e64 s[14:15], v10, v8
	s_and_b64 vcc, s[10:11], exec
	s_cselect_b64 s[12:13], s[14:15], s[12:13]
	v_cndmask_b32_e64 v203, 0, 1.0, s[12:13]
	v_add_u32_e32 v10, 8, v9
	v_cmp_le_u32_e64 s[12:13], v10, v8
	v_cmp_ge_u32_e64 s[14:15], v10, v8
	s_and_b64 vcc, s[10:11], exec
	s_cselect_b64 s[12:13], s[14:15], s[12:13]
	v_cndmask_b32_e64 v204, 0, 1.0, s[12:13]
	v_add_u32_e32 v10, 12, v9
	v_cmp_le_u32_e64 s[12:13], v10, v8
	v_cmp_ge_u32_e64 s[14:15], v10, v8
	s_and_b64 vcc, s[10:11], exec
	s_cselect_b64 s[12:13], s[14:15], s[12:13]
	v_cndmask_b32_e64 v205, 0, 1.0, s[12:13]
	v_and_b32_e32 v9, 15, v200
	v_lshl_add_u32 v8, v9, 4, s33
	v_lshl_add_u32 v9, v9, 2, s33
	ds_read_b128 v[232:235], v8
	ds_read_b128 v[236:239], v8 offset:256
	ds_read_b128 v[240:243], v8 offset:512
	ds_read_b128 v[244:247], v8 offset:768
	ds_read_b128 v[248:251], v8 offset:1024
	ds_read_b128 v[210:213], v8 offset:1280
	ds_read_b128 v[214:217], v8 offset:1536
	ds_read_b128 v[218:221], v8 offset:1792
	ds_read_b128 v[222:225], v8 offset:2048
	ds_read_b128 v[226:229], v8 offset:2304
	ds_read_b32 v230, v9 offset:2560
	s_waitcnt vmcnt(0) lgkmcnt(0)
	s_branch .LBB0_489

; __device__ __forceinline__ void rwkv_chain(LAS unsigned char* lds, int cid, const bf16_t* P0, const float* mu, const float* w0, const float* w2, const float* a0, const float* a2, ...
;     ...
;         __syncthreads();
;         { RW_IDS if (tid < 64) { float lw[32];
; #pragma unroll
;             for (int s = 0; s < 32; ++s) lw[s] = wS[(dir ? 31 - s : s) * 64 + tid];
; #pragma unroll
;             for (int s = 1; s < 32; ++s) lw[s] += lw[s - 1];
; #pragma unroll
;             for (int s = 0; s < 32; ++s) wS[(dir ? 31 - s : s) * 64 + tid] = lw[s]; } }
;         __syncthreads();
.LBB0_514:
	s_or_b64 exec, exec, s[12:13]
	v_mov_b32_e32 v8, v200
	s_waitcnt lgkmcnt(0)
	s_barrier
	s_nop 0
	v_readfirstlane_b32 s7, v8
	s_lshr_b32 s7, s7, 6
	s_mov_b64 s[12:13], exec
	s_cmp_gt_u32 s7, 3
	s_cbranch_scc1 .LBB0_516
	v_and_b32_e32 v9, 15, v8
	v_bfe_u32 v10, v8, 4, 2
	v_lshl_or_b32 v9, s7, 4, v9
	v_lshlrev_b32_e32 v9, 2, v9
	v_lshl_add_u32 v11, v10, 8, v9
	v_lshl_add_u32 v12, v10, 10, v9
	ds_read_b32 v114, v11 offset:24576
	ds_read_b32 v115, v11 offset:25600
	ds_read_b32 v116, v11 offset:26624
	ds_read_b32 v117, v11 offset:27648
	ds_read_b32 v118, v11 offset:28672
	ds_read_b32 v119, v11 offset:29696
	ds_read_b32 v120, v11 offset:30720
	ds_read_b32 v121, v11 offset:31744
	s_and_b64 vcc, exec, s[10:11]
	s_cbranch_vccnz .Lrw_cum_rev
	s_waitcnt lgkmcnt(7)
	v_mfma_f32_16x16x4_f32 v[16:19], v202, v114, 0
	v_mfma_f32_16x16x4_f32 v[20:23], v201, v114, 0
	s_waitcnt lgkmcnt(6)
	v_mfma_f32_16x16x4_f32 v[16:19], v203, v115, v[16:19]
	v_mfma_f32_16x16x4_f32 v[20:23], v201, v115, v[20:23]
	s_waitcnt lgkmcnt(5)
	v_mfma_f32_16x16x4_f32 v[16:19], v204, v116, v[16:19]
	v_mfma_f32_16x16x4_f32 v[20:23], v201, v116, v[20:23]
	s_waitcnt lgkmcnt(4)
	v_mfma_f32_16x16x4_f32 v[16:19], v205, v117, v[16:19]
	v_mfma_f32_16x16x4_f32 v[20:23], v201, v117, v[20:23]
	s_waitcnt lgkmcnt(3)
	v_mfma_f32_16x16x4_f32 v[20:23], v202, v118, v[20:23]
	s_waitcnt lgkmcnt(2)
	v_mfma_f32_16x16x4_f32 v[20:23], v203, v119, v[20:23]
	s_waitcnt lgkmcnt(1)
	v_mfma_f32_16x16x4_f32 v[20:23], v204, v120, v[20:23]
	s_waitcnt lgkmcnt(0)
	v_mfma_f32_16x16x4_f32 v[20:23], v205, v121, v[20:23]
	s_nop 9
	ds_write_b32 v12, v16 offset:24576
	ds_write_b32 v12, v17 offset:24832
	ds_write_b32 v12, v18 offset:25088
	ds_write_b32 v12, v19 offset:25344
	ds_write_b32 v12, v20 offset:28672
	ds_write_b32 v12, v21 offset:28928
	ds_write_b32 v12, v22 offset:29184
	ds_write_b32 v12, v23 offset:29440
	s_branch .LBB0_516
.Lrw_cum_rev:
	s_waitcnt lgkmcnt(7)
	v_mfma_f32_16x16x4_f32 v[16:19], v202, v114, 0
	s_waitcnt lgkmcnt(6)
	v_mfma_f32_16x16x4_f32 v[16:19], v203, v115, v[16:19]
	s_waitcnt lgkmcnt(5)
	v_mfma_f32_16x16x4_f32 v[16:19], v204, v116, v[16:19]
	s_waitcnt lgkmcnt(4)
	v_mfma_f32_16x16x4_f32 v[16:19], v205, v117, v[16:19]
	s_waitcnt lgkmcnt(3)
	v_mfma_f32_16x16x4_f32 v[16:19], v201, v118, v[16:19]
	v_mfma_f32_16x16x4_f32 v[20:23], v202, v118, 0
	s_waitcnt lgkmcnt(2)
	v_mfma_f32_16x16x4_f32 v[16:19], v201, v119, v[16:19]
	v_mfma_f32_16x16x4_f32 v[20:23], v203, v119, v[20:23]
	s_waitcnt lgkmcnt(1)
	v_mfma_f32_16x16x4_f32 v[16:19], v201, v120, v[16:19]
	v_mfma_f32_16x16x4_f32 v[20:23], v204, v120, v[20:23]
	s_waitcnt lgkmcnt(0)
	v_mfma_f32_16x16x4_f32 v[16:19], v201, v121, v[16:19]
	v_mfma_f32_16x16x4_f32 v[20:23], v205, v121, v[20:23]
	s_nop 9
	ds_write_b32 v12, v16 offset:24576
	ds_write_b32 v12, v17 offset:24832
	ds_write_b32 v12, v18 offset:25088
	ds_write_b32 v12, v19 offset:25344
	ds_write_b32 v12, v20 offset:28672
	ds_write_b32 v12, v21 offset:28928
	ds_write_b32 v12, v22 offset:29184
	ds_write_b32 v12, v23 offset:29440
